# attention: v18 plus tail-loop G prefetch with packed subtracts and the value-preserving VALU trims (all bit-identical edits stacked)
# speedup vs baseline: 1.0014x; 1.0014x over previous
.LBB0_1341:
	v_sub_f32_e32 v0, v214, v217
	s_waitcnt lgkmcnt(4)
	v_pk_add_f32 v[110:111], v[0:1], v[222:223] op_sel_hi:[0,1] neg_lo:[0,1] neg_hi:[0,1]
	v_pk_add_f32 v[108:109], v[0:1], v[220:221] op_sel_hi:[0,1] neg_lo:[0,1] neg_hi:[0,1]
	v_pk_add_f32 v[106:107], v[0:1], v[198:199] op_sel_hi:[0,1] neg_lo:[0,1] neg_hi:[0,1]
	v_pk_add_f32 v[104:105], v[0:1], v[196:197] op_sel_hi:[0,1] neg_lo:[0,1] neg_hi:[0,1]
	v_pk_add_f32 v[102:103], v[0:1], v[194:195] op_sel_hi:[0,1] neg_lo:[0,1] neg_hi:[0,1]
	v_pk_add_f32 v[100:101], v[0:1], v[192:193] op_sel_hi:[0,1] neg_lo:[0,1] neg_hi:[0,1]
	v_pk_add_f32 v[98:99], v[0:1], v[190:191] op_sel_hi:[0,1] neg_lo:[0,1] neg_hi:[0,1]
	v_pk_add_f32 v[96:97], v[0:1], v[188:189] op_sel_hi:[0,1] neg_lo:[0,1] neg_hi:[0,1]
	s_waitcnt lgkmcnt(0)
	v_pk_add_f32 v[94:95], v[0:1], v[238:239] op_sel_hi:[0,1] neg_lo:[0,1] neg_hi:[0,1]
	v_pk_add_f32 v[92:93], v[0:1], v[236:237] op_sel_hi:[0,1] neg_lo:[0,1] neg_hi:[0,1]
	v_pk_add_f32 v[90:91], v[0:1], v[234:235] op_sel_hi:[0,1] neg_lo:[0,1] neg_hi:[0,1]
	v_pk_add_f32 v[88:89], v[0:1], v[232:233] op_sel_hi:[0,1] neg_lo:[0,1] neg_hi:[0,1]
	v_pk_add_f32 v[86:87], v[0:1], v[230:231] op_sel_hi:[0,1] neg_lo:[0,1] neg_hi:[0,1]
	v_pk_add_f32 v[84:85], v[0:1], v[228:229] op_sel_hi:[0,1] neg_lo:[0,1] neg_hi:[0,1]
	v_pk_add_f32 v[82:83], v[0:1], v[226:227] op_sel_hi:[0,1] neg_lo:[0,1] neg_hi:[0,1]
	v_pk_add_f32 v[80:81], v[0:1], v[224:225] op_sel_hi:[0,1] neg_lo:[0,1] neg_hi:[0,1]
	ds_read_b128 v[188:191], v180 offset:256
	ds_read_b128 v[192:195], v180 offset:288
	ds_read_b128 v[196:199], v180 offset:320
	ds_read_b128 v[220:223], v180 offset:352
	ds_read_b128 v[224:227], v180 offset:384
	ds_read_b128 v[228:231], v180 offset:416
	ds_read_b128 v[232:235], v180 offset:448
	ds_read_b128 v[236:239], v180 offset:480
	v_add_u32_e32 v0, s8, v216
	ds_read_b64_tr_b16 v[4:5], v0 offset:24576
	ds_read_b64_tr_b16 v[6:7], v0 offset:25088
	v_mfma_f32_32x32x16_bf16 v[96:111], v[172:175], v[124:127], v[96:111]
	v_add_f32_e32 v1, v64, v65
	v_add_f32_e32 v1, v66, v1
	v_add_f32_e32 v1, v67, v1
	v_add_f32_e32 v1, v68, v1
	v_add_f32_e32 v1, v69, v1
	v_cvt_pk_bf16_f32 v140, v64, v65
	v_cvt_pk_bf16_f32 v141, v66, v67
	ds_read_b64_tr_b16 v[8:9], v0 offset:28672
	ds_read_b64_tr_b16 v[10:11], v0 offset:29184
	v_mfma_f32_32x32x16_bf16 v[80:95], v[168:171], v[124:127], v[80:95]
	v_add_f32_e32 v1, v70, v1
	v_add_f32_e32 v1, v71, v1
	v_add_f32_e32 v1, v72, v1
	v_add_f32_e32 v1, v73, v1
	v_cvt_pk_bf16_f32 v142, v68, v69
	v_cvt_pk_bf16_f32 v143, v70, v71
	ds_read_b64_tr_b16 v[12:13], v0 offset:25600
	ds_read_b64_tr_b16 v[14:15], v0 offset:26112
	v_mfma_f32_32x32x16_bf16 v[96:111], v[164:167], v[120:123], v[96:111]
	v_add_f32_e32 v1, v74, v1
	v_add_f32_e32 v1, v75, v1
	v_add_f32_e32 v1, v76, v1
	v_add_f32_e32 v1, v77, v1
	v_cvt_pk_bf16_f32 v136, v72, v73
	v_cvt_pk_bf16_f32 v137, v74, v75
	ds_read_b64_tr_b16 v[64:65], v0 offset:29696
	ds_read_b64_tr_b16 v[66:67], v0 offset:30208
	v_mfma_f32_32x32x16_bf16 v[80:95], v[160:163], v[120:123], v[80:95]
	v_add_f32_e32 v1, v78, v1
	v_add_f32_e32 v1, v79, v1
	v_add_f32_e32 v1, v48, v1
	v_add_f32_e32 v1, v49, v1
	v_cvt_pk_bf16_f32 v138, v76, v77
	v_cvt_pk_bf16_f32 v139, v78, v79
	ds_read_b64_tr_b16 v[68:69], v0 offset:26624
	ds_read_b64_tr_b16 v[70:71], v0 offset:27136
	v_mfma_f32_32x32x16_bf16 v[96:111], v[156:159], v[116:119], v[96:111]
	v_add_f32_e32 v1, v50, v1
	v_add_f32_e32 v1, v51, v1
	v_add_f32_e32 v1, v52, v1
	v_add_f32_e32 v1, v53, v1
	v_cvt_pk_bf16_f32 v132, v48, v49
	v_cvt_pk_bf16_f32 v133, v50, v51
	ds_read_b64_tr_b16 v[48:49], v0 offset:30720
	ds_read_b64_tr_b16 v[50:51], v0 offset:31232
	v_mfma_f32_32x32x16_bf16 v[80:95], v[152:155], v[116:119], v[80:95]
	v_add_f32_e32 v1, v54, v1
	v_add_f32_e32 v1, v55, v1
	v_add_f32_e32 v1, v56, v1
	v_add_f32_e32 v1, v57, v1
	v_cvt_pk_bf16_f32 v134, v52, v53
	v_cvt_pk_bf16_f32 v135, v54, v55
	ds_read_b64_tr_b16 v[52:53], v0 offset:27648
	ds_read_b64_tr_b16 v[54:55], v0 offset:28160
	v_mfma_f32_32x32x16_bf16 v[96:111], v[148:151], v[112:115], v[96:111]
	v_add_f32_e32 v1, v58, v1
	v_add_f32_e32 v1, v59, v1
	v_add_f32_e32 v1, v60, v1
	v_add_f32_e32 v1, v61, v1
	v_cvt_pk_bf16_f32 v128, v56, v57
	v_cvt_pk_bf16_f32 v129, v58, v59
	ds_read_b64_tr_b16 v[56:57], v0 offset:31744
	ds_read_b64_tr_b16 v[58:59], v0 offset:32256
	v_mfma_f32_32x32x16_bf16 v[80:95], v[144:147], v[112:115], v[80:95]
	v_add_f32_e32 v0, v62, v1
	v_add_f32_e32 v2, v63, v0
	v_cvt_pk_bf16_f32 v130, v60, v61
	v_cvt_pk_bf16_f32 v131, v62, v63
	s_mov_b32 s8, 0xfffe0000
	s_mov_b32 s9, -1
	v_lshl_add_u64 v[0:1], v[178:179], 0, s[8:9]
	s_add_i32 s0, s16, s21
	s_mov_b32 s4, m0
	s_mov_b32 m0, s0
	s_nop 0
	global_load_lds_dwordx4 v[0:1], off
	s_mov_b32 m0, s4
	v_lshl_add_u64 v[0:1], v[176:177], 0, s[8:9]
	s_add_i32 s0, s14, s22
	s_mov_b32 s4, m0
	s_mov_b32 m0, s0
	s_nop 0
	global_load_lds_dwordx4 v[0:1], off
	s_mov_b32 m0, s4
	v_max_f32_e32 v0, v96, v97
	v_max3_f32 v1, v98, v99, v81
	v_max3_f32 v0, v0, v80, v82
	v_max3_f32 v0, v0, v83, v100
	v_max3_f32 v1, v1, v102, v103
	v_max3_f32 v0, v0, v101, v84
	v_max3_f32 v1, v1, v86, v87
	v_max3_f32 v0, v0, v85, v104
	v_max3_f32 v1, v1, v106, v107
	v_max3_f32 v0, v0, v105, v88
	v_max3_f32 v1, v1, v90, v91
	v_max3_f32 v0, v0, v89, v108
	v_max3_f32 v1, v1, v110, v111
	v_max3_f32 v60, v0, v109, v92
	v_max3_f32 v1, v1, v94, v95
	v_max3_f32 v1, v60, v93, v1
	v_add_f32_e32 v0, v218, v2
	v_mov_b32_e32 v2, v1
	s_nop 1
	v_permlane32_swap_b32_e32 v1, v2
	v_max_f32_e32 v1, v1, v2
	v_cmp_lt_f32_e32 vcc, s33, v1
	s_cmp_lg_u64 vcc, 0
	s_cselect_b64 s[8:9], -1, 0
	s_cbranch_vccnz .LBB0_1349

.LBB0_1344:
	s_add_i32 s0, s14, 0x2000
	s_cmpk_lg_i32 s14, 0x4000
	s_cselect_b32 s25, s0, 0
	v_sub_f32_e32 v1, v214, v217
	s_waitcnt lgkmcnt(4)
	v_pk_add_f32 v[78:79], v[0:1], v[222:223] op_sel:[1,0] op_sel_hi:[1,1] neg_lo:[0,1] neg_hi:[0,1]
	v_pk_add_f32 v[76:77], v[0:1], v[220:221] op_sel:[1,0] op_sel_hi:[1,1] neg_lo:[0,1] neg_hi:[0,1]
	v_pk_add_f32 v[74:75], v[0:1], v[198:199] op_sel:[1,0] op_sel_hi:[1,1] neg_lo:[0,1] neg_hi:[0,1]
	v_pk_add_f32 v[72:73], v[0:1], v[196:197] op_sel:[1,0] op_sel_hi:[1,1] neg_lo:[0,1] neg_hi:[0,1]
	v_pk_add_f32 v[70:71], v[0:1], v[194:195] op_sel:[1,0] op_sel_hi:[1,1] neg_lo:[0,1] neg_hi:[0,1]
	v_pk_add_f32 v[68:69], v[0:1], v[192:193] op_sel:[1,0] op_sel_hi:[1,1] neg_lo:[0,1] neg_hi:[0,1]
	v_pk_add_f32 v[66:67], v[0:1], v[190:191] op_sel:[1,0] op_sel_hi:[1,1] neg_lo:[0,1] neg_hi:[0,1]
	v_pk_add_f32 v[64:65], v[0:1], v[188:189] op_sel:[1,0] op_sel_hi:[1,1] neg_lo:[0,1] neg_hi:[0,1]
	s_waitcnt lgkmcnt(0)
	v_pk_add_f32 v[62:63], v[0:1], v[238:239] op_sel:[1,0] op_sel_hi:[1,1] neg_lo:[0,1] neg_hi:[0,1]
	v_pk_add_f32 v[60:61], v[0:1], v[236:237] op_sel:[1,0] op_sel_hi:[1,1] neg_lo:[0,1] neg_hi:[0,1]
	v_pk_add_f32 v[58:59], v[0:1], v[234:235] op_sel:[1,0] op_sel_hi:[1,1] neg_lo:[0,1] neg_hi:[0,1]
	v_pk_add_f32 v[56:57], v[0:1], v[232:233] op_sel:[1,0] op_sel_hi:[1,1] neg_lo:[0,1] neg_hi:[0,1]
	v_pk_add_f32 v[54:55], v[0:1], v[230:231] op_sel:[1,0] op_sel_hi:[1,1] neg_lo:[0,1] neg_hi:[0,1]
	v_pk_add_f32 v[52:53], v[0:1], v[228:229] op_sel:[1,0] op_sel_hi:[1,1] neg_lo:[0,1] neg_hi:[0,1]
	v_pk_add_f32 v[50:51], v[0:1], v[226:227] op_sel:[1,0] op_sel_hi:[1,1] neg_lo:[0,1] neg_hi:[0,1]
	v_pk_add_f32 v[48:49], v[0:1], v[224:225] op_sel:[1,0] op_sel_hi:[1,1] neg_lo:[0,1] neg_hi:[0,1]
	ds_read_b128 v[188:191], v180 offset:512
	ds_read_b128 v[192:195], v180 offset:544
	ds_read_b128 v[196:199], v180 offset:576
	ds_read_b128 v[220:223], v180 offset:608
	ds_read_b128 v[224:227], v180 offset:640
	ds_read_b128 v[228:231], v180 offset:672
	ds_read_b128 v[232:235], v180 offset:704
	ds_read_b128 v[236:239], v180 offset:736
	v_add_u32_e32 v1, s16, v216
	ds_read_b64_tr_b16 v[152:153], v1 offset:24576
	ds_read_b64_tr_b16 v[154:155], v1 offset:25088
	v_mfma_f32_32x32x16_bf16 v[64:79], v[164:167], v[124:127], v[64:79]
	v_add_f32_e32 v2, v96, v97
	v_add_f32_e32 v2, v98, v2
	v_add_f32_e32 v2, v99, v2
	v_add_f32_e32 v2, v100, v2
	v_add_f32_e32 v2, v101, v2
	v_cvt_pk_bf16_f32 v140, v96, v97
	v_cvt_pk_bf16_f32 v141, v98, v99
	ds_read_b64_tr_b16 v[96:97], v1 offset:28672
	ds_read_b64_tr_b16 v[98:99], v1 offset:29184
	v_mfma_f32_32x32x16_bf16 v[48:63], v[160:163], v[124:127], v[48:63]
	v_add_f32_e32 v2, v102, v2
	v_add_f32_e32 v2, v103, v2
	v_add_f32_e32 v2, v104, v2
	v_add_f32_e32 v2, v105, v2
	v_cvt_pk_bf16_f32 v142, v100, v101
	v_cvt_pk_bf16_f32 v143, v102, v103
	ds_read_b64_tr_b16 v[100:101], v1 offset:25600
	ds_read_b64_tr_b16 v[102:103], v1 offset:26112
	v_mfma_f32_32x32x16_bf16 v[64:79], v[156:159], v[120:123], v[64:79]
	v_add_f32_e32 v2, v106, v2
	v_add_f32_e32 v2, v107, v2
	v_add_f32_e32 v2, v108, v2
	v_add_f32_e32 v2, v109, v2
	v_cvt_pk_bf16_f32 v136, v104, v105
	v_cvt_pk_bf16_f32 v137, v106, v107
	ds_read_b64_tr_b16 v[104:105], v1 offset:29696
	ds_read_b64_tr_b16 v[106:107], v1 offset:30208
	v_mfma_f32_32x32x16_bf16 v[48:63], v[148:151], v[120:123], v[48:63]
	v_add_f32_e32 v2, v110, v2
	v_add_f32_e32 v2, v111, v2
	v_add_f32_e32 v2, v80, v2
	v_add_f32_e32 v2, v81, v2
	v_cvt_pk_bf16_f32 v138, v108, v109
	v_cvt_pk_bf16_f32 v139, v110, v111
	ds_read_b64_tr_b16 v[108:109], v1 offset:26624
	ds_read_b64_tr_b16 v[110:111], v1 offset:27136
	v_mfma_f32_32x32x16_bf16 v[64:79], v[144:147], v[116:119], v[64:79]
	v_add_f32_e32 v2, v82, v2
	v_add_f32_e32 v2, v83, v2
	v_add_f32_e32 v2, v84, v2
	v_add_f32_e32 v2, v85, v2
	v_cvt_pk_bf16_f32 v132, v80, v81
	v_cvt_pk_bf16_f32 v133, v82, v83
	ds_read_b64_tr_b16 v[80:81], v1 offset:30720
	ds_read_b64_tr_b16 v[82:83], v1 offset:31232
	v_mfma_f32_32x32x16_bf16 v[48:63], v[12:15], v[116:119], v[48:63]
	v_add_f32_e32 v2, v86, v2
	v_add_f32_e32 v2, v87, v2
	v_add_f32_e32 v2, v88, v2
	v_add_f32_e32 v2, v89, v2
	v_cvt_pk_bf16_f32 v134, v84, v85
	v_cvt_pk_bf16_f32 v135, v86, v87
	ds_read_b64_tr_b16 v[12:13], v1 offset:27648
	ds_read_b64_tr_b16 v[14:15], v1 offset:28160
	v_mfma_f32_32x32x16_bf16 v[64:79], v[8:11], v[112:115], v[64:79]
	v_add_f32_e32 v2, v90, v2
	v_add_f32_e32 v2, v91, v2
	v_add_f32_e32 v2, v92, v2
	v_add_f32_e32 v2, v93, v2
	v_cvt_pk_bf16_f32 v128, v88, v89
	v_cvt_pk_bf16_f32 v129, v90, v91
	ds_read_b64_tr_b16 v[8:9], v1 offset:31744
	ds_read_b64_tr_b16 v[10:11], v1 offset:32256
	v_mfma_f32_32x32x16_bf16 v[48:63], v[4:7], v[112:115], v[48:63]
	v_add_f32_e32 v1, v94, v2
	v_add_f32_e32 v1, v95, v1
	v_cvt_pk_bf16_f32 v130, v92, v93
	v_cvt_pk_bf16_f32 v131, v94, v95
	v_max_f32_e32 v2, v64, v65
	s_nop 6
	v_max3_f32 v4, v66, v67, v49
	v_max3_f32 v2, v2, v48, v50
	v_max3_f32 v2, v2, v51, v68
	v_max3_f32 v4, v4, v70, v71
	v_max3_f32 v2, v2, v69, v52
	v_max3_f32 v4, v4, v54, v55
	v_max3_f32 v2, v2, v53, v72
	v_max3_f32 v4, v4, v74, v75
	v_max3_f32 v2, v2, v73, v56
	v_max3_f32 v4, v4, v58, v59
	v_max3_f32 v2, v2, v57, v76
	v_max3_f32 v4, v4, v78, v79
	v_max3_f32 v2, v2, v77, v60
	v_max3_f32 v4, v4, v62, v63
	v_add_f32_e32 v218, v0, v1
	v_max3_f32 v0, v2, v61, v4
	v_mov_b32_e32 v1, v0
	s_nop 1
	v_permlane32_swap_b32_e32 v0, v1
	s_add_i32 s0, s14, s21
	s_mov_b32 s4, m0
	s_mov_b32 m0, s0
	s_nop 0
	global_load_lds_dwordx4 v[178:179], off
	s_mov_b32 m0, s4
	v_max_f32_e32 v0, v0, v1
	s_add_i32 s0, s25, s22
	s_mov_b32 s4, m0
	s_mov_b32 m0, s0
	s_nop 0
	global_load_lds_dwordx4 v[176:177], off
	s_mov_b32 m0, s4
	v_cmp_lt_f32_e32 vcc, s33, v0
	s_cmp_lg_u64 vcc, 0
	s_cselect_b64 s[8:9], -1, 0
	s_cbranch_vccnz .LBB0_1352

.LBB0_1366:
	v_sub_f32_e32 v2, v214, v217
	s_waitcnt lgkmcnt(4)
	v_pk_add_f32 v[110:111], v[2:3], v[222:223] op_sel_hi:[0,1] neg_lo:[0,1] neg_hi:[0,1]
	v_pk_add_f32 v[108:109], v[2:3], v[220:221] op_sel_hi:[0,1] neg_lo:[0,1] neg_hi:[0,1]
	v_pk_add_f32 v[106:107], v[2:3], v[198:199] op_sel_hi:[0,1] neg_lo:[0,1] neg_hi:[0,1]
	v_pk_add_f32 v[104:105], v[2:3], v[196:197] op_sel_hi:[0,1] neg_lo:[0,1] neg_hi:[0,1]
	v_pk_add_f32 v[102:103], v[2:3], v[194:195] op_sel_hi:[0,1] neg_lo:[0,1] neg_hi:[0,1]
	v_pk_add_f32 v[100:101], v[2:3], v[192:193] op_sel_hi:[0,1] neg_lo:[0,1] neg_hi:[0,1]
	v_pk_add_f32 v[98:99], v[2:3], v[190:191] op_sel_hi:[0,1] neg_lo:[0,1] neg_hi:[0,1]
	v_pk_add_f32 v[96:97], v[2:3], v[188:189] op_sel_hi:[0,1] neg_lo:[0,1] neg_hi:[0,1]
	s_waitcnt lgkmcnt(0)
	v_pk_add_f32 v[94:95], v[2:3], v[238:239] op_sel_hi:[0,1] neg_lo:[0,1] neg_hi:[0,1]
	v_pk_add_f32 v[92:93], v[2:3], v[236:237] op_sel_hi:[0,1] neg_lo:[0,1] neg_hi:[0,1]
	v_pk_add_f32 v[90:91], v[2:3], v[234:235] op_sel_hi:[0,1] neg_lo:[0,1] neg_hi:[0,1]
	v_pk_add_f32 v[88:89], v[2:3], v[232:233] op_sel_hi:[0,1] neg_lo:[0,1] neg_hi:[0,1]
	v_pk_add_f32 v[86:87], v[2:3], v[230:231] op_sel_hi:[0,1] neg_lo:[0,1] neg_hi:[0,1]
	v_pk_add_f32 v[84:85], v[2:3], v[228:229] op_sel_hi:[0,1] neg_lo:[0,1] neg_hi:[0,1]
	v_pk_add_f32 v[82:83], v[2:3], v[226:227] op_sel_hi:[0,1] neg_lo:[0,1] neg_hi:[0,1]
	v_pk_add_f32 v[80:81], v[2:3], v[224:225] op_sel_hi:[0,1] neg_lo:[0,1] neg_hi:[0,1]
	ds_read_b128 v[188:191], v1 offset:256
	ds_read_b128 v[192:195], v1 offset:288
	ds_read_b128 v[196:199], v1 offset:320
	ds_read_b128 v[220:223], v1 offset:352
	ds_read_b128 v[224:227], v1 offset:384
	ds_read_b128 v[228:231], v1 offset:416
	ds_read_b128 v[232:235], v1 offset:448
	ds_read_b128 v[236:239], v1 offset:480
	v_add_u32_e32 v2, s14, v216
	ds_read_b64_tr_b16 v[4:5], v2 offset:24576
	ds_read_b64_tr_b16 v[6:7], v2 offset:25088
	v_mfma_f32_32x32x16_bf16 v[96:111], v[172:175], v[124:127], v[96:111]
	v_add_f32_e32 v8, v64, v65
	v_add_f32_e32 v8, v66, v8
	v_add_f32_e32 v8, v67, v8
	v_add_f32_e32 v8, v68, v8
	v_add_f32_e32 v12, v69, v8
	v_cvt_pk_bf16_f32 v140, v64, v65
	v_cvt_pk_bf16_f32 v141, v66, v67
	ds_read_b64_tr_b16 v[8:9], v2 offset:28672
	ds_read_b64_tr_b16 v[10:11], v2 offset:29184
	v_mfma_f32_32x32x16_bf16 v[80:95], v[168:171], v[124:127], v[80:95]
	v_add_f32_e32 v12, v70, v12
	v_add_f32_e32 v12, v71, v12
	v_add_f32_e32 v12, v72, v12
	v_add_f32_e32 v64, v73, v12
	v_cvt_pk_bf16_f32 v142, v68, v69
	v_cvt_pk_bf16_f32 v143, v70, v71
	ds_read_b64_tr_b16 v[12:13], v2 offset:25600
	ds_read_b64_tr_b16 v[14:15], v2 offset:26112
	v_mfma_f32_32x32x16_bf16 v[96:111], v[164:167], v[120:123], v[96:111]
	v_add_f32_e32 v64, v74, v64
	v_add_f32_e32 v64, v75, v64
	v_add_f32_e32 v64, v76, v64
	v_add_f32_e32 v68, v77, v64
	v_cvt_pk_bf16_f32 v136, v72, v73
	v_cvt_pk_bf16_f32 v137, v74, v75
	ds_read_b64_tr_b16 v[64:65], v2 offset:29696
	ds_read_b64_tr_b16 v[66:67], v2 offset:30208
	v_mfma_f32_32x32x16_bf16 v[80:95], v[160:163], v[120:123], v[80:95]
	v_add_f32_e32 v68, v78, v68
	v_add_f32_e32 v68, v79, v68
	v_add_f32_e32 v68, v48, v68
	v_add_f32_e32 v72, v49, v68
	v_cvt_pk_bf16_f32 v138, v76, v77
	v_cvt_pk_bf16_f32 v139, v78, v79
	ds_read_b64_tr_b16 v[68:69], v2 offset:26624
	ds_read_b64_tr_b16 v[70:71], v2 offset:27136
	v_mfma_f32_32x32x16_bf16 v[96:111], v[156:159], v[116:119], v[96:111]
	v_add_f32_e32 v72, v50, v72
	v_add_f32_e32 v72, v51, v72
	v_add_f32_e32 v72, v52, v72
	v_add_f32_e32 v72, v53, v72
	v_cvt_pk_bf16_f32 v132, v48, v49
	v_cvt_pk_bf16_f32 v133, v50, v51
	ds_read_b64_tr_b16 v[48:49], v2 offset:30720
	ds_read_b64_tr_b16 v[50:51], v2 offset:31232
	v_mfma_f32_32x32x16_bf16 v[80:95], v[152:155], v[116:119], v[80:95]
	v_add_f32_e32 v72, v54, v72
	v_add_f32_e32 v72, v55, v72
	v_add_f32_e32 v72, v56, v72
	v_add_f32_e32 v72, v57, v72
	v_cvt_pk_bf16_f32 v134, v52, v53
	v_cvt_pk_bf16_f32 v135, v54, v55
	ds_read_b64_tr_b16 v[52:53], v2 offset:27648
	ds_read_b64_tr_b16 v[54:55], v2 offset:28160
	v_mfma_f32_32x32x16_bf16 v[96:111], v[148:151], v[112:115], v[96:111]
	v_add_f32_e32 v72, v58, v72
	v_add_f32_e32 v72, v59, v72
	v_add_f32_e32 v72, v60, v72
	v_add_f32_e32 v72, v61, v72
	v_cvt_pk_bf16_f32 v128, v56, v57
	v_cvt_pk_bf16_f32 v129, v58, v59
	ds_read_b64_tr_b16 v[56:57], v2 offset:31744
	ds_read_b64_tr_b16 v[58:59], v2 offset:32256
	v_mfma_f32_32x32x16_bf16 v[80:95], v[144:147], v[112:115], v[80:95]
	v_add_f32_e32 v2, v62, v72
	v_add_f32_e32 v2, v63, v2
	v_add_f32_e32 v2, 0, v2
	v_cvt_pk_bf16_f32 v130, v60, v61
	v_cvt_pk_bf16_f32 v131, v62, v63
	s_add_i32 s64, s10, 1
	s_cmp_ge_i32 s64, s24
	s_cselect_b64 s[8:9], -1, 0
	s_and_b64 vcc, exec, s[8:9]
	s_cbranch_vccnz .LBB0_1368
	s_lshl_b64 s[4:5], s[64:65], 17
	v_lshl_add_u64 v[60:61], v[200:201], 0, s[4:5]
	s_add_i32 s4, s25, s21
	s_mov_b32 s5, m0
	s_mov_b32 m0, s4
	s_nop 0
	global_load_lds_dwordx4 v[60:61], off
	s_mov_b32 m0, s5

.LBB0_1375:
	v_sub_f32_e32 v128, v214, v217
	s_waitcnt lgkmcnt(4)
	v_pk_add_f32 v[78:79], v[128:129], v[222:223] op_sel_hi:[0,1] neg_lo:[0,1] neg_hi:[0,1]
	v_pk_add_f32 v[76:77], v[128:129], v[220:221] op_sel_hi:[0,1] neg_lo:[0,1] neg_hi:[0,1]
	v_pk_add_f32 v[74:75], v[128:129], v[198:199] op_sel_hi:[0,1] neg_lo:[0,1] neg_hi:[0,1]
	v_pk_add_f32 v[72:73], v[128:129], v[196:197] op_sel_hi:[0,1] neg_lo:[0,1] neg_hi:[0,1]
	v_pk_add_f32 v[70:71], v[128:129], v[194:195] op_sel_hi:[0,1] neg_lo:[0,1] neg_hi:[0,1]
	v_pk_add_f32 v[68:69], v[128:129], v[192:193] op_sel_hi:[0,1] neg_lo:[0,1] neg_hi:[0,1]
	v_pk_add_f32 v[66:67], v[128:129], v[190:191] op_sel_hi:[0,1] neg_lo:[0,1] neg_hi:[0,1]
	v_pk_add_f32 v[64:65], v[128:129], v[188:189] op_sel_hi:[0,1] neg_lo:[0,1] neg_hi:[0,1]
	s_waitcnt lgkmcnt(0)
	v_pk_add_f32 v[62:63], v[128:129], v[238:239] op_sel_hi:[0,1] neg_lo:[0,1] neg_hi:[0,1]
	v_pk_add_f32 v[60:61], v[128:129], v[236:237] op_sel_hi:[0,1] neg_lo:[0,1] neg_hi:[0,1]
	v_pk_add_f32 v[58:59], v[128:129], v[234:235] op_sel_hi:[0,1] neg_lo:[0,1] neg_hi:[0,1]
	v_pk_add_f32 v[56:57], v[128:129], v[232:233] op_sel_hi:[0,1] neg_lo:[0,1] neg_hi:[0,1]
	v_pk_add_f32 v[54:55], v[128:129], v[230:231] op_sel_hi:[0,1] neg_lo:[0,1] neg_hi:[0,1]
	v_pk_add_f32 v[52:53], v[128:129], v[228:229] op_sel_hi:[0,1] neg_lo:[0,1] neg_hi:[0,1]
	v_pk_add_f32 v[50:51], v[128:129], v[226:227] op_sel_hi:[0,1] neg_lo:[0,1] neg_hi:[0,1]
	v_pk_add_f32 v[48:49], v[128:129], v[224:225] op_sel_hi:[0,1] neg_lo:[0,1] neg_hi:[0,1]
	ds_read_b128 v[188:191], v1 offset:512
	ds_read_b128 v[192:195], v1 offset:544
	ds_read_b128 v[196:199], v1 offset:576
	ds_read_b128 v[220:223], v1 offset:608
	ds_read_b128 v[224:227], v1 offset:640
	ds_read_b128 v[228:231], v1 offset:672
	ds_read_b128 v[232:235], v1 offset:704
	ds_read_b128 v[236:239], v1 offset:736
	v_add_u32_e32 v6, s25, v216
	ds_read_b64_tr_b16 v[184:185], v6 offset:24576
	ds_read_b64_tr_b16 v[186:187], v6 offset:25088
	v_mfma_f32_32x32x16_bf16 v[64:79], v[172:175], v[124:127], v[64:79]
	v_add_f32_e32 v4, v96, v97
	v_add_f32_e32 v4, v98, v4
	v_add_f32_e32 v4, v99, v4
	v_add_f32_e32 v4, v100, v4
	v_add_f32_e32 v4, v101, v4
	v_cvt_pk_bf16_f32 v140, v96, v97
	v_cvt_pk_bf16_f32 v141, v98, v99
	ds_read_b64_tr_b16 v[180:181], v6 offset:28672
	ds_read_b64_tr_b16 v[182:183], v6 offset:29184
	v_mfma_f32_32x32x16_bf16 v[48:63], v[168:171], v[124:127], v[48:63]
	v_add_f32_e32 v4, v102, v4
	v_add_f32_e32 v4, v103, v4
	v_add_f32_e32 v4, v104, v4
	v_add_f32_e32 v4, v105, v4
	v_cvt_pk_bf16_f32 v142, v100, v101
	v_cvt_pk_bf16_f32 v143, v102, v103
	ds_read_b64_tr_b16 v[176:177], v6 offset:25600
	ds_read_b64_tr_b16 v[178:179], v6 offset:26112
	v_mfma_f32_32x32x16_bf16 v[64:79], v[164:167], v[120:123], v[64:79]
	v_add_f32_e32 v4, v106, v4
	v_add_f32_e32 v4, v107, v4
	v_add_f32_e32 v4, v108, v4
	v_add_f32_e32 v4, v109, v4
	v_cvt_pk_bf16_f32 v136, v104, v105
	v_cvt_pk_bf16_f32 v137, v106, v107
	ds_read_b64_tr_b16 v[100:101], v6 offset:29696
	ds_read_b64_tr_b16 v[102:103], v6 offset:30208
	v_mfma_f32_32x32x16_bf16 v[48:63], v[160:163], v[120:123], v[48:63]
	v_add_f32_e32 v4, v110, v4
	v_add_f32_e32 v4, v111, v4
	v_add_f32_e32 v4, v80, v4
	v_add_f32_e32 v4, v81, v4
	v_cvt_pk_bf16_f32 v138, v108, v109
	v_cvt_pk_bf16_f32 v139, v110, v111
	ds_read_b64_tr_b16 v[96:97], v6 offset:26624
	ds_read_b64_tr_b16 v[98:99], v6 offset:27136
	v_mfma_f32_32x32x16_bf16 v[64:79], v[156:159], v[116:119], v[64:79]
	v_add_f32_e32 v4, v82, v4
	v_add_f32_e32 v4, v83, v4
	v_add_f32_e32 v4, v84, v4
	v_add_f32_e32 v4, v85, v4
	v_cvt_pk_bf16_f32 v132, v80, v81
	v_cvt_pk_bf16_f32 v133, v82, v83
	ds_read_b64_tr_b16 v[12:13], v6 offset:30720
	ds_read_b64_tr_b16 v[14:15], v6 offset:31232
	v_mfma_f32_32x32x16_bf16 v[48:63], v[152:155], v[116:119], v[48:63]
	v_add_f32_e32 v4, v86, v4
	v_add_f32_e32 v4, v87, v4
	v_add_f32_e32 v4, v88, v4
	v_add_f32_e32 v4, v89, v4
	v_cvt_pk_bf16_f32 v134, v84, v85
	v_cvt_pk_bf16_f32 v135, v86, v87
	ds_read_b64_tr_b16 v[8:9], v6 offset:27648
	ds_read_b64_tr_b16 v[10:11], v6 offset:28160
	v_mfma_f32_32x32x16_bf16 v[64:79], v[148:151], v[112:115], v[64:79]
	v_add_f32_e32 v4, v90, v4
	v_add_f32_e32 v4, v91, v4
	v_add_f32_e32 v4, v92, v4
	v_add_f32_e32 v80, v93, v4
	v_cvt_pk_bf16_f32 v128, v88, v89
	v_cvt_pk_bf16_f32 v129, v90, v91
	ds_read_b64_tr_b16 v[4:5], v6 offset:31744
	ds_read_b64_tr_b16 v[6:7], v6 offset:32256
	v_mfma_f32_32x32x16_bf16 v[48:63], v[144:147], v[112:115], v[48:63]
	v_add_f32_e32 v80, v94, v80
	v_add_f32_e32 v80, v95, v80
	v_add_f32_e32 v80, 0, v80
	v_cvt_pk_bf16_f32 v130, v92, v93
	v_cvt_pk_bf16_f32 v131, v94, v95
	s_add_i32 s64, s10, 2
	s_cmp_ge_i32 s64, s24
	s_cselect_b64 s[12:13], -1, 0
	s_and_b64 vcc, exec, s[12:13]
	s_cbranch_vccnz .LBB0_1377
	s_lshl_b64 s[4:5], s[64:65], 17
	v_lshl_add_u64 v[82:83], v[200:201], 0, s[4:5]
	s_add_i32 s4, s0, s21
	s_mov_b32 s5, m0
	s_mov_b32 m0, s4
	s_nop 0
	global_load_lds_dwordx4 v[82:83], off
	s_mov_b32 m0, s5
